# P4 group-norm loop: next iteration's 16 row loads software-prefetched into spare VGPRs during the current rows' normalisation
# baseline (speedup 1.0000x reference)
.LBB0_744:
	v_lshl_add_u64 v[4:5], v[2:3], 0, s[30:31]
	v_add_co_u32_e32 v6, vcc, 0x10800000, v4
	v_lshl_add_u64 v[8:9], v[0:1], 0, s[30:31]
	s_nop 0
	v_addc_co_u32_e32 v7, vcc, 0, v5, vcc
	v_add_co_u32_e32 v32, vcc, 0x18800000, v8
	flat_load_dwordx2 v[26:27], v[6:7]
	s_nop 0
	v_addc_co_u32_e32 v33, vcc, 0, v9, vcc
	flat_load_dwordx2 v[38:39], v[32:33]
	flat_load_dwordx2 v[40:41], v[6:7] offset:2048
	flat_load_dwordx2 v[42:43], v[32:33] offset:2048
	v_add_co_u32_e32 v6, vcc, 0x10801000, v4
	s_mov_b32 s20, 0x358637bd
	s_nop 0
	v_addc_co_u32_e32 v7, vcc, 0, v5, vcc
	v_add_co_u32_e32 v20, vcc, 0x18801000, v8
	flat_load_dwordx2 v[34:35], v[6:7]
	s_nop 0
	v_addc_co_u32_e32 v21, vcc, 0, v9, vcc
	flat_load_dwordx2 v[36:37], v[20:21]
	flat_load_dwordx2 v[30:31], v[6:7] offset:2048
	flat_load_dwordx2 v[28:29], v[20:21] offset:2048
	v_add_co_u32_e32 v6, vcc, 0x10802000, v4
	s_add_u32 s30, s30, 0x4000
	s_nop 0
	v_addc_co_u32_e32 v7, vcc, 0, v5, vcc
	v_add_co_u32_e32 v10, vcc, 0x18802000, v8
	flat_load_dwordx2 v[22:23], v[6:7]
	s_nop 0
	v_addc_co_u32_e32 v11, vcc, 0, v9, vcc
	flat_load_dwordx2 v[24:25], v[10:11]
	flat_load_dwordx2 v[18:19], v[6:7] offset:2048
	flat_load_dwordx2 v[16:17], v[10:11] offset:2048
	v_add_co_u32_e32 v6, vcc, 0x10803000, v4
	s_addc_u32 s31, s31, 0
	s_nop 0
	v_addc_co_u32_e32 v7, vcc, 0, v5, vcc
	v_add_co_u32_e32 v4, vcc, 0x18803000, v8
	flat_load_dwordx2 v[12:13], v[6:7]
	s_nop 0
	v_addc_co_u32_e32 v5, vcc, 0, v9, vcc
	flat_load_dwordx2 v[14:15], v[4:5]
	flat_load_dwordx2 v[8:9], v[6:7] offset:2048
	s_nop 0
	flat_load_dwordx2 v[6:7], v[4:5] offset:2048
	s_cmp_lg_u32 s30, 0x10000
	s_waitcnt vmcnt(0) lgkmcnt(0)
	s_cbranch_scc0 .Lgpf_skip_a
	v_lshl_add_u64 v[130:131], v[2:3], 0, s[30:31]
	v_add_co_u32_e32 v242, vcc, 0x10800000, v130
	v_lshl_add_u64 v[240:241], v[0:1], 0, s[30:31]
	s_nop 0
	v_addc_co_u32_e32 v243, vcc, 0, v131, vcc
	v_add_co_u32_e32 v134, vcc, 0x18800000, v240
	global_load_dwordx2 v[206:207], v[242:243], off
	s_nop 0
	v_addc_co_u32_e32 v135, vcc, 0, v241, vcc
	global_load_dwordx2 v[208:209], v[134:135], off
	global_load_dwordx2 v[210:211], v[242:243], off offset:2048
	global_load_dwordx2 v[216:217], v[134:135], off offset:2048
	v_add_co_u32_e32 v242, vcc, 0x10801000, v130
	s_nop 0
	v_addc_co_u32_e32 v243, vcc, 0, v131, vcc
	v_add_co_u32_e32 v136, vcc, 0x18801000, v240
	global_load_dwordx2 v[218:219], v[242:243], off
	s_nop 0
	v_addc_co_u32_e32 v137, vcc, 0, v241, vcc
	global_load_dwordx2 v[220:221], v[136:137], off
	global_load_dwordx2 v[222:223], v[242:243], off offset:2048
	global_load_dwordx2 v[224:225], v[136:137], off offset:2048
	v_add_co_u32_e32 v242, vcc, 0x10802000, v130
	s_nop 0
	v_addc_co_u32_e32 v243, vcc, 0, v131, vcc
	v_add_co_u32_e32 v138, vcc, 0x18802000, v240
	global_load_dwordx2 v[226:227], v[242:243], off
	s_nop 0
	v_addc_co_u32_e32 v139, vcc, 0, v241, vcc
	global_load_dwordx2 v[228:229], v[138:139], off
	global_load_dwordx2 v[230:231], v[242:243], off offset:2048
	global_load_dwordx2 v[232:233], v[138:139], off offset:2048
	v_add_co_u32_e32 v242, vcc, 0x10803000, v130
	s_nop 0
	v_addc_co_u32_e32 v243, vcc, 0, v131, vcc
	v_add_co_u32_e32 v130, vcc, 0x18803000, v240
	global_load_dwordx2 v[234:235], v[242:243], off
	s_nop 0
	v_addc_co_u32_e32 v131, vcc, 0, v241, vcc
	global_load_dwordx2 v[236:237], v[130:131], off
	global_load_dwordx2 v[240:241], v[242:243], off offset:2048
	s_nop 0
	global_load_dwordx2 v[242:243], v[130:131], off offset:2048
.Lgpf_skip_a:
	v_and_b32_e32 v45, 0xffff0000, v27
	v_and_b32_e32 v47, 0xffff0000, v39
	v_lshlrev_b32_e32 v46, 16, v39
	v_and_b32_e32 v39, 0xffff0000, v38
	v_lshlrev_b32_e32 v38, 16, v38
	v_mul_f32_e32 v52, 0xbfb8aa3b, v46
	v_mul_f32_e32 v53, 0xbfb8aa3b, v47
	v_and_b32_e32 v55, 0xffff0000, v43
	v_lshlrev_b32_e32 v54, 16, v43
	v_and_b32_e32 v43, 0xffff0000, v42
	v_lshlrev_b32_e32 v42, 16, v42
	v_mul_f32_e32 v48, 0xbfb8aa3b, v38
	v_mul_f32_e32 v49, 0xbfb8aa3b, v39
	v_exp_f32_e32 v52, v52
	v_exp_f32_e32 v53, v53
	v_mul_f32_e32 v56, 0xbfb8aa3b, v42
	v_mul_f32_e32 v57, 0xbfb8aa3b, v43
	v_exp_f32_e32 v48, v48
	v_exp_f32_e32 v49, v49
	v_exp_f32_e32 v56, v56
	v_exp_f32_e32 v57, v57
	v_add_f32_e32 v52, 1.0, v52
	v_add_f32_e32 v53, 1.0, v53
	v_add_f32_e32 v48, 1.0, v48
	v_add_f32_e32 v49, 1.0, v49
	v_rcp_f32_e32 v52, v52
	v_rcp_f32_e32 v53, v53
	v_add_f32_e32 v56, 1.0, v56
	v_add_f32_e32 v57, 1.0, v57
	v_rcp_f32_e32 v48, v48
	v_rcp_f32_e32 v49, v49
	v_rcp_f32_e32 v56, v56
	v_rcp_f32_e32 v57, v57
	v_lshlrev_b32_e32 v44, 16, v27
	v_and_b32_e32 v27, 0xffff0000, v26
	v_lshlrev_b32_e32 v26, 16, v26
	v_pk_mul_f32 v[46:47], v[52:53], v[46:47]
	v_and_b32_e32 v53, 0xffff0000, v41
	v_lshlrev_b32_e32 v52, 16, v41
	v_and_b32_e32 v41, 0xffff0000, v40
	v_lshlrev_b32_e32 v40, 16, v40
	v_pk_mul_f32 v[38:39], v[48:49], v[38:39]
	v_add_f32_e32 v48, v27, v26
	v_pk_mul_f32 v[42:43], v[56:57], v[42:43]
	v_add_f32_e32 v56, v41, v40
	v_add_f32_e32 v48, v48, v44
	v_add_f32_e32 v56, v56, v52
	v_add_f32_e32 v48, v48, v45
	v_add_f32_e32 v56, v56, v53
	s_nop 1
	v_add_f32_dpp v48, v48, v48 quad_perm:[1,0,3,2] row_mask:0xf bank_mask:0xf
	v_add_f32_dpp v56, v56, v56 quad_perm:[1,0,3,2] row_mask:0xf bank_mask:0xf
	s_nop 1
	v_add_f32_dpp v48, v48, v48 quad_perm:[2,3,0,1] row_mask:0xf bank_mask:0xf
	v_add_f32_dpp v56, v56, v56 quad_perm:[2,3,0,1] row_mask:0xf bank_mask:0xf
	s_nop 1
	v_add_f32_dpp v48, v48, v48 row_half_mirror row_mask:0xf bank_mask:0xf
	v_add_f32_dpp v56, v56, v56 row_half_mirror row_mask:0xf bank_mask:0xf
	s_nop 1
	v_add_f32_dpp v48, v48, v48 row_mirror row_mask:0xf bank_mask:0xf
	v_add_f32_dpp v56, v56, v56 row_mirror row_mask:0xf bank_mask:0xf
	v_mov_b32_e32 v49, v48
	v_mov_b32_e32 v57, v56
	s_nop 1
	v_permlane16_swap_b32_e32 v48, v49
	v_permlane16_swap_b32_e32 v56, v57
	v_add_f32_e32 v48, v48, v49
	v_add_f32_e32 v56, v56, v57
	v_mov_b32_e32 v49, v48
	v_mov_b32_e32 v57, v56
	s_nop 1
	v_permlane32_swap_b32_e32 v48, v49
	v_permlane32_swap_b32_e32 v56, v57
	v_add_f32_e32 v48, v48, v49
	v_add_f32_e32 v56, v56, v57
	v_mul_f32_e32 v48, 0x3b800000, v48
	v_mul_f32_e32 v56, 0x3b800000, v56
	v_pk_add_f32 v[50:51], v[26:27], v[48:49] op_sel_hi:[1,0] neg_lo:[0,1] neg_hi:[0,1]
	v_pk_add_f32 v[40:41], v[40:41], v[56:57] op_sel_hi:[1,0] neg_lo:[0,1] neg_hi:[0,1]
	v_pk_add_f32 v[44:45], v[44:45], v[48:49] op_sel_hi:[1,0] neg_lo:[0,1] neg_hi:[0,1]
	v_pk_mul_f32 v[26:27], v[50:51], v[50:51]
	v_pk_add_f32 v[52:53], v[52:53], v[56:57] op_sel_hi:[1,0] neg_lo:[0,1] neg_hi:[0,1]
	v_pk_mul_f32 v[56:57], v[40:41], v[40:41]
	v_pk_mul_f32 v[48:49], v[44:45], v[44:45]
	v_pk_mul_f32 v[58:59], v[52:53], v[52:53]
	v_mov_b32_e32 v60, v56
	v_mov_b32_e32 v61, v26
	v_mov_b32_e32 v26, v57
	v_pk_add_f32 v[26:27], v[60:61], v[26:27]
	v_mov_b32_e32 v56, v58
	v_mov_b32_e32 v57, v48
	v_pk_add_f32 v[26:27], v[56:57], v[26:27]
	v_mov_b32_e32 v48, v59
	v_pk_add_f32 v[26:27], v[48:49], v[26:27]
	s_nop 1
	v_add_f32_dpp v26, v26, v26 quad_perm:[1,0,3,2] row_mask:0xf bank_mask:0xf
	v_add_f32_dpp v27, v27, v27 quad_perm:[1,0,3,2] row_mask:0xf bank_mask:0xf
	s_nop 1
	v_add_f32_dpp v26, v26, v26 quad_perm:[2,3,0,1] row_mask:0xf bank_mask:0xf
	v_add_f32_dpp v27, v27, v27 quad_perm:[2,3,0,1] row_mask:0xf bank_mask:0xf
	s_nop 1
	v_add_f32_dpp v26, v26, v26 row_half_mirror row_mask:0xf bank_mask:0xf
	v_add_f32_dpp v27, v27, v27 row_half_mirror row_mask:0xf bank_mask:0xf
	s_nop 1
	v_add_f32_dpp v26, v26, v26 row_mirror row_mask:0xf bank_mask:0xf
	v_add_f32_dpp v27, v27, v27 row_mirror row_mask:0xf bank_mask:0xf
	v_mov_b32_e32 v48, v26
	v_mov_b32_e32 v49, v27
	s_nop 1
	v_permlane16_swap_b32_e32 v26, v48
	v_permlane16_swap_b32_e32 v27, v49
	v_add_f32_e32 v26, v26, v48
	v_add_f32_e32 v27, v27, v49
	v_mov_b32_e32 v48, v26
	v_mov_b32_e32 v49, v27
	s_nop 1
	v_permlane32_swap_b32_e32 v26, v48
	v_permlane32_swap_b32_e32 v27, v49
	v_add_f32_e32 v48, v26, v48
	v_add_f32_e32 v49, v27, v49
	v_mov_b64_e32 v[26:27], s[20:21]
	v_pk_fma_f32 v[48:49], v[48:49], s[28:29], v[26:27] op_sel_hi:[1,0,0]
	s_nop 0
	v_mul_f32_e32 v56, 0x4b800000, v49
	v_cmp_gt_f32_e32 vcc, s39, v49
	v_cmp_gt_f32_e64 s[20:21], s39, v48
	s_nop 0
	v_cndmask_b32_e32 v49, v49, v56, vcc
	v_rsq_f32_e32 v49, v49
	s_nop 0
	v_mul_f32_e32 v56, 0x45800000, v49
	v_cndmask_b32_e32 v56, v49, v56, vcc
	v_pk_mul_f32 v[50:51], v[50:51], v[56:57] op_sel_hi:[1,0]
	v_pk_mul_f32 v[44:45], v[44:45], v[56:57] op_sel_hi:[1,0]
	v_pk_mul_f32 v[38:39], v[38:39], v[50:51]
	v_pk_mul_f32 v[44:45], v[46:47], v[44:45]
	v_cvt_pk_bf16_f32 v38, v38, v39
	v_cvt_pk_bf16_f32 v39, v44, v45
	flat_store_dwordx2 v[32:33], v[38:39]
	v_mul_f32_e32 v38, 0x4b800000, v48
	v_cndmask_b32_e64 v38, v48, v38, s[20:21]
	v_rsq_f32_e32 v38, v38
	v_and_b32_e32 v47, 0xffff0000, v29
	v_lshlrev_b32_e32 v46, 16, v29
	v_and_b32_e32 v29, 0xffff0000, v28
	v_mul_f32_e32 v39, 0x45800000, v38
	v_cndmask_b32_e64 v38, v38, v39, s[20:21]
	v_pk_mul_f32 v[40:41], v[40:41], v[38:39] op_sel_hi:[1,0]
	v_mul_f32_e32 v39, 0xbfb8aa3b, v54
	v_pk_mul_f32 v[40:41], v[42:43], v[40:41]
	v_mul_f32_e32 v43, 0xbfb8aa3b, v55
	v_exp_f32_e32 v39, v39
	v_exp_f32_e32 v43, v43
	v_cvt_pk_bf16_f32 v40, v40, v41
	v_lshlrev_b32_e32 v28, 16, v28
	v_add_f32_e32 v39, 1.0, v39
	v_add_f32_e32 v43, 1.0, v43
	v_rcp_f32_e32 v42, v39
	v_rcp_f32_e32 v43, v43
	v_pk_mul_f32 v[38:39], v[52:53], v[38:39] op_sel_hi:[1,0]
	v_mul_f32_e32 v48, 0xbfb8aa3b, v28
	v_mul_f32_e32 v49, 0xbfb8aa3b, v29
	v_pk_mul_f32 v[42:43], v[42:43], v[54:55]
	v_exp_f32_e32 v48, v48
	v_pk_mul_f32 v[38:39], v[42:43], v[38:39]
	v_exp_f32_e32 v49, v49
	v_cvt_pk_bf16_f32 v41, v38, v39
	v_and_b32_e32 v39, 0xffff0000, v37
	v_lshlrev_b32_e32 v38, 16, v37
	v_and_b32_e32 v37, 0xffff0000, v36
	v_lshlrev_b32_e32 v36, 16, v36
	v_mul_f32_e32 v44, 0xbfb8aa3b, v38
	v_mul_f32_e32 v45, 0xbfb8aa3b, v39
	flat_store_dwordx2 v[32:33], v[40:41] offset:2048
	v_mul_f32_e32 v40, 0xbfb8aa3b, v36
	v_mul_f32_e32 v41, 0xbfb8aa3b, v37
	v_exp_f32_e32 v44, v44
	v_exp_f32_e32 v45, v45
	v_exp_f32_e32 v40, v40
	v_exp_f32_e32 v41, v41
	v_add_f32_e32 v44, 1.0, v44
	v_add_f32_e32 v45, 1.0, v45
	v_add_f32_e32 v40, 1.0, v40
	v_add_f32_e32 v41, 1.0, v41
	v_rcp_f32_e32 v44, v44
	v_rcp_f32_e32 v45, v45
	v_add_f32_e32 v48, 1.0, v48
	v_add_f32_e32 v49, 1.0, v49
	v_rcp_f32_e32 v40, v40
	v_rcp_f32_e32 v41, v41
	v_rcp_f32_e32 v48, v48
	v_rcp_f32_e32 v49, v49
	v_and_b32_e32 v33, 0xffff0000, v35
	v_lshlrev_b32_e32 v32, 16, v35
	v_and_b32_e32 v35, 0xffff0000, v34
	v_lshlrev_b32_e32 v34, 16, v34
	v_pk_mul_f32 v[38:39], v[44:45], v[38:39]
	v_and_b32_e32 v45, 0xffff0000, v31
	v_lshlrev_b32_e32 v44, 16, v31
	v_and_b32_e32 v31, 0xffff0000, v30
	v_lshlrev_b32_e32 v30, 16, v30
	v_pk_mul_f32 v[36:37], v[40:41], v[36:37]
	v_add_f32_e32 v40, v35, v34
	v_pk_mul_f32 v[28:29], v[48:49], v[28:29]
	v_add_f32_e32 v48, v31, v30
	v_add_f32_e32 v40, v40, v32
	v_add_f32_e32 v48, v48, v44
	v_add_f32_e32 v40, v40, v33
	v_add_f32_e32 v48, v48, v45
	s_nop 1
	v_add_f32_dpp v40, v40, v40 quad_perm:[1,0,3,2] row_mask:0xf bank_mask:0xf
	v_add_f32_dpp v48, v48, v48 quad_perm:[1,0,3,2] row_mask:0xf bank_mask:0xf
	s_nop 1
	v_add_f32_dpp v40, v40, v40 quad_perm:[2,3,0,1] row_mask:0xf bank_mask:0xf
	v_add_f32_dpp v48, v48, v48 quad_perm:[2,3,0,1] row_mask:0xf bank_mask:0xf
	s_nop 1
	v_add_f32_dpp v40, v40, v40 row_half_mirror row_mask:0xf bank_mask:0xf
	v_add_f32_dpp v48, v48, v48 row_half_mirror row_mask:0xf bank_mask:0xf
	s_nop 1
	v_add_f32_dpp v40, v40, v40 row_mirror row_mask:0xf bank_mask:0xf
	v_add_f32_dpp v48, v48, v48 row_mirror row_mask:0xf bank_mask:0xf
	v_mov_b32_e32 v41, v40
	v_mov_b32_e32 v49, v48
	s_nop 1
	v_permlane16_swap_b32_e32 v40, v41
	v_permlane16_swap_b32_e32 v48, v49
	v_add_f32_e32 v40, v40, v41
	v_add_f32_e32 v48, v48, v49
	v_mov_b32_e32 v41, v40
	v_mov_b32_e32 v49, v48
	s_nop 1
	v_permlane32_swap_b32_e32 v40, v41
	v_permlane32_swap_b32_e32 v48, v49
	v_add_f32_e32 v40, v40, v41
	v_add_f32_e32 v48, v48, v49
	v_mul_f32_e32 v40, 0x3b800000, v40
	v_mul_f32_e32 v48, 0x3b800000, v48
	v_pk_add_f32 v[34:35], v[34:35], v[40:41] op_sel_hi:[1,0] neg_lo:[0,1] neg_hi:[0,1]
	v_pk_add_f32 v[30:31], v[30:31], v[48:49] op_sel_hi:[1,0] neg_lo:[0,1] neg_hi:[0,1]
	v_pk_add_f32 v[32:33], v[32:33], v[40:41] op_sel_hi:[1,0] neg_lo:[0,1] neg_hi:[0,1]
	v_pk_mul_f32 v[40:41], v[34:35], v[34:35]
	v_pk_add_f32 v[44:45], v[44:45], v[48:49] op_sel_hi:[1,0] neg_lo:[0,1] neg_hi:[0,1]
	v_pk_mul_f32 v[48:49], v[30:31], v[30:31]
	v_pk_mul_f32 v[42:43], v[32:33], v[32:33]
	v_pk_mul_f32 v[50:51], v[44:45], v[44:45]
	v_mov_b32_e32 v52, v48
	v_mov_b32_e32 v53, v40
	v_mov_b32_e32 v40, v49
	v_pk_add_f32 v[40:41], v[52:53], v[40:41]
	v_mov_b32_e32 v48, v50
	v_mov_b32_e32 v49, v42
	v_pk_add_f32 v[40:41], v[48:49], v[40:41]
	v_mov_b32_e32 v42, v51
	v_pk_add_f32 v[40:41], v[42:43], v[40:41]
	s_nop 1
	v_add_f32_dpp v40, v40, v40 quad_perm:[1,0,3,2] row_mask:0xf bank_mask:0xf
	v_add_f32_dpp v41, v41, v41 quad_perm:[1,0,3,2] row_mask:0xf bank_mask:0xf
	s_nop 1
	v_add_f32_dpp v40, v40, v40 quad_perm:[2,3,0,1] row_mask:0xf bank_mask:0xf
	v_add_f32_dpp v41, v41, v41 quad_perm:[2,3,0,1] row_mask:0xf bank_mask:0xf
	s_nop 1
	v_add_f32_dpp v40, v40, v40 row_half_mirror row_mask:0xf bank_mask:0xf
	v_add_f32_dpp v41, v41, v41 row_half_mirror row_mask:0xf bank_mask:0xf
	s_nop 1
	v_add_f32_dpp v40, v40, v40 row_mirror row_mask:0xf bank_mask:0xf
	v_add_f32_dpp v41, v41, v41 row_mirror row_mask:0xf bank_mask:0xf
	v_mov_b32_e32 v42, v40
	v_mov_b32_e32 v43, v41
	s_nop 1
	v_permlane16_swap_b32_e32 v40, v42
	v_permlane16_swap_b32_e32 v41, v43
	v_add_f32_e32 v40, v40, v42
	v_add_f32_e32 v41, v41, v43
	v_mov_b32_e32 v42, v40
	v_mov_b32_e32 v43, v41
	s_nop 1
	v_permlane32_swap_b32_e32 v40, v42
	v_permlane32_swap_b32_e32 v41, v43
	v_add_f32_e32 v40, v40, v42
	v_add_f32_e32 v41, v41, v43
	s_nop 0
	v_pk_fma_f32 v[40:41], v[40:41], s[28:29], v[26:27] op_sel_hi:[1,0,0]
	s_nop 0
	v_mul_f32_e32 v42, 0x4b800000, v41
	v_cmp_gt_f32_e64 s[20:21], s39, v41
	v_cmp_gt_f32_e32 vcc, s39, v40
	s_nop 0
	v_cndmask_b32_e64 v41, v41, v42, s[20:21]
	v_rsq_f32_e32 v41, v41
	s_nop 0
	v_mul_f32_e32 v42, 0x45800000, v41
	v_cndmask_b32_e64 v42, v41, v42, s[20:21]
	v_pk_mul_f32 v[34:35], v[34:35], v[42:43] op_sel_hi:[1,0]
	v_pk_mul_f32 v[32:33], v[32:33], v[42:43] op_sel_hi:[1,0]
	v_pk_mul_f32 v[34:35], v[36:37], v[34:35]
	v_pk_mul_f32 v[32:33], v[38:39], v[32:33]
	v_cvt_pk_bf16_f32 v34, v34, v35
	v_cvt_pk_bf16_f32 v35, v32, v33
	v_mul_f32_e32 v32, 0x4b800000, v40
	v_cndmask_b32_e32 v32, v40, v32, vcc
	v_rsq_f32_e32 v32, v32
	flat_store_dwordx2 v[20:21], v[34:35]
	v_and_b32_e32 v37, 0xffff0000, v17
	v_lshlrev_b32_e32 v36, 16, v17
	v_mul_f32_e32 v33, 0x45800000, v32
	v_cndmask_b32_e32 v32, v32, v33, vcc
	v_pk_mul_f32 v[30:31], v[30:31], v[32:33] op_sel_hi:[1,0]
	v_pk_mul_f32 v[32:33], v[44:45], v[32:33] op_sel_hi:[1,0]
	v_pk_mul_f32 v[28:29], v[28:29], v[30:31]
	v_mul_f32_e32 v30, 0xbfb8aa3b, v46
	v_mul_f32_e32 v31, 0xbfb8aa3b, v47
	v_exp_f32_e32 v30, v30
	v_exp_f32_e32 v31, v31
	v_cvt_pk_bf16_f32 v28, v28, v29
	v_and_b32_e32 v17, 0xffff0000, v16
	v_add_f32_e32 v30, 1.0, v30
	v_add_f32_e32 v31, 1.0, v31
	v_rcp_f32_e32 v30, v30
	v_rcp_f32_e32 v31, v31
	v_lshlrev_b32_e32 v16, 16, v16
	v_mul_f32_e32 v38, 0xbfb8aa3b, v16
	v_mul_f32_e32 v39, 0xbfb8aa3b, v17
	v_pk_mul_f32 v[30:31], v[30:31], v[46:47]
	v_exp_f32_e32 v38, v38
	v_pk_mul_f32 v[30:31], v[30:31], v[32:33]
	v_exp_f32_e32 v39, v39
	v_cvt_pk_bf16_f32 v29, v30, v31
	flat_store_dwordx2 v[20:21], v[28:29] offset:2048
	v_and_b32_e32 v29, 0xffff0000, v25
	v_lshlrev_b32_e32 v28, 16, v25
	v_and_b32_e32 v25, 0xffff0000, v24
	v_lshlrev_b32_e32 v24, 16, v24
	v_mul_f32_e32 v34, 0xbfb8aa3b, v28
	v_mul_f32_e32 v35, 0xbfb8aa3b, v29
	v_mul_f32_e32 v30, 0xbfb8aa3b, v24
	v_mul_f32_e32 v31, 0xbfb8aa3b, v25
	v_exp_f32_e32 v34, v34
	v_exp_f32_e32 v35, v35
	v_exp_f32_e32 v30, v30
	v_exp_f32_e32 v31, v31
	v_add_f32_e32 v34, 1.0, v34
	v_add_f32_e32 v35, 1.0, v35
	v_add_f32_e32 v30, 1.0, v30
	v_add_f32_e32 v31, 1.0, v31
	v_rcp_f32_e32 v34, v34
	v_rcp_f32_e32 v35, v35
	v_add_f32_e32 v38, 1.0, v38
	v_add_f32_e32 v39, 1.0, v39
	v_rcp_f32_e32 v30, v30
	v_rcp_f32_e32 v31, v31
	v_rcp_f32_e32 v38, v38
	v_rcp_f32_e32 v39, v39
	v_and_b32_e32 v21, 0xffff0000, v23
	v_lshlrev_b32_e32 v20, 16, v23
	v_and_b32_e32 v23, 0xffff0000, v22
	v_lshlrev_b32_e32 v22, 16, v22
	v_pk_mul_f32 v[28:29], v[34:35], v[28:29]
	v_and_b32_e32 v35, 0xffff0000, v19
	v_lshlrev_b32_e32 v34, 16, v19
	v_and_b32_e32 v19, 0xffff0000, v18
	v_lshlrev_b32_e32 v18, 16, v18
	v_pk_mul_f32 v[24:25], v[30:31], v[24:25]
	v_add_f32_e32 v30, v23, v22
	v_pk_mul_f32 v[16:17], v[38:39], v[16:17]
	v_add_f32_e32 v38, v19, v18
	v_add_f32_e32 v30, v30, v20
	v_add_f32_e32 v38, v38, v34
	v_add_f32_e32 v30, v30, v21
	v_add_f32_e32 v38, v38, v35
	s_nop 1
	v_add_f32_dpp v30, v30, v30 quad_perm:[1,0,3,2] row_mask:0xf bank_mask:0xf
	v_add_f32_dpp v38, v38, v38 quad_perm:[1,0,3,2] row_mask:0xf bank_mask:0xf
	s_nop 1
	v_add_f32_dpp v30, v30, v30 quad_perm:[2,3,0,1] row_mask:0xf bank_mask:0xf
	v_add_f32_dpp v38, v38, v38 quad_perm:[2,3,0,1] row_mask:0xf bank_mask:0xf
	s_nop 1
	v_add_f32_dpp v30, v30, v30 row_half_mirror row_mask:0xf bank_mask:0xf
	v_add_f32_dpp v38, v38, v38 row_half_mirror row_mask:0xf bank_mask:0xf
	s_nop 1
	v_add_f32_dpp v30, v30, v30 row_mirror row_mask:0xf bank_mask:0xf
	v_add_f32_dpp v38, v38, v38 row_mirror row_mask:0xf bank_mask:0xf
	v_mov_b32_e32 v31, v30
	v_mov_b32_e32 v39, v38
	s_nop 1
	v_permlane16_swap_b32_e32 v30, v31
	v_permlane16_swap_b32_e32 v38, v39
	v_add_f32_e32 v30, v30, v31
	v_add_f32_e32 v38, v38, v39
	v_mov_b32_e32 v31, v30
	v_mov_b32_e32 v39, v38
	s_nop 1
	v_permlane32_swap_b32_e32 v30, v31
	v_permlane32_swap_b32_e32 v38, v39
	v_add_f32_e32 v30, v30, v31
	v_add_f32_e32 v38, v38, v39
	v_mul_f32_e32 v30, 0x3b800000, v30
	v_mul_f32_e32 v38, 0x3b800000, v38
	v_pk_add_f32 v[22:23], v[22:23], v[30:31] op_sel_hi:[1,0] neg_lo:[0,1] neg_hi:[0,1]
	v_pk_add_f32 v[18:19], v[18:19], v[38:39] op_sel_hi:[1,0] neg_lo:[0,1] neg_hi:[0,1]
	v_pk_add_f32 v[20:21], v[20:21], v[30:31] op_sel_hi:[1,0] neg_lo:[0,1] neg_hi:[0,1]
	v_pk_mul_f32 v[30:31], v[22:23], v[22:23]
	v_pk_add_f32 v[34:35], v[34:35], v[38:39] op_sel_hi:[1,0] neg_lo:[0,1] neg_hi:[0,1]
	v_pk_mul_f32 v[38:39], v[18:19], v[18:19]
	v_pk_mul_f32 v[32:33], v[20:21], v[20:21]
	v_pk_mul_f32 v[40:41], v[34:35], v[34:35]
	v_mov_b32_e32 v42, v38
	v_mov_b32_e32 v43, v30
	v_mov_b32_e32 v30, v39
	v_pk_add_f32 v[30:31], v[42:43], v[30:31]
	v_mov_b32_e32 v38, v40
	v_mov_b32_e32 v39, v32
	v_pk_add_f32 v[30:31], v[38:39], v[30:31]
	v_mov_b32_e32 v32, v41
	v_pk_add_f32 v[30:31], v[32:33], v[30:31]
	s_nop 1
	v_add_f32_dpp v30, v30, v30 quad_perm:[1,0,3,2] row_mask:0xf bank_mask:0xf
	v_add_f32_dpp v31, v31, v31 quad_perm:[1,0,3,2] row_mask:0xf bank_mask:0xf
	s_nop 1
	v_add_f32_dpp v30, v30, v30 quad_perm:[2,3,0,1] row_mask:0xf bank_mask:0xf
	v_add_f32_dpp v31, v31, v31 quad_perm:[2,3,0,1] row_mask:0xf bank_mask:0xf
	s_nop 1
	v_add_f32_dpp v30, v30, v30 row_half_mirror row_mask:0xf bank_mask:0xf
	v_add_f32_dpp v31, v31, v31 row_half_mirror row_mask:0xf bank_mask:0xf
	s_nop 1
	v_add_f32_dpp v30, v30, v30 row_mirror row_mask:0xf bank_mask:0xf
	v_add_f32_dpp v31, v31, v31 row_mirror row_mask:0xf bank_mask:0xf
	v_mov_b32_e32 v32, v30
	v_mov_b32_e32 v33, v31
	s_nop 1
	v_permlane16_swap_b32_e32 v30, v32
	v_permlane16_swap_b32_e32 v31, v33
	v_add_f32_e32 v30, v30, v32
	v_add_f32_e32 v31, v31, v33
	v_mov_b32_e32 v32, v30
	v_mov_b32_e32 v33, v31
	s_nop 1
	v_permlane32_swap_b32_e32 v30, v32
	v_permlane32_swap_b32_e32 v31, v33
	v_add_f32_e32 v30, v30, v32
	v_add_f32_e32 v31, v31, v33
	s_nop 0
	v_pk_fma_f32 v[30:31], v[30:31], s[28:29], v[26:27] op_sel_hi:[1,0,0]
	s_nop 0
	v_mul_f32_e32 v32, 0x4b800000, v31
	v_cmp_gt_f32_e64 s[20:21], s39, v31
	v_cmp_gt_f32_e32 vcc, s39, v30
	s_nop 0
	v_cndmask_b32_e64 v31, v31, v32, s[20:21]
	v_rsq_f32_e32 v31, v31
	s_nop 0
	v_mul_f32_e32 v32, 0x45800000, v31
	v_cndmask_b32_e64 v32, v31, v32, s[20:21]
	v_pk_mul_f32 v[22:23], v[22:23], v[32:33] op_sel_hi:[1,0]
	v_pk_mul_f32 v[20:21], v[20:21], v[32:33] op_sel_hi:[1,0]
	v_pk_mul_f32 v[22:23], v[24:25], v[22:23]
	v_pk_mul_f32 v[20:21], v[28:29], v[20:21]
	v_cvt_pk_bf16_f32 v22, v22, v23
	v_cvt_pk_bf16_f32 v23, v20, v21
	v_mul_f32_e32 v20, 0x4b800000, v30
	v_cndmask_b32_e32 v20, v30, v20, vcc
	v_rsq_f32_e32 v20, v20
	flat_store_dwordx2 v[10:11], v[22:23]
	v_and_b32_e32 v25, 0xffff0000, v7
	v_lshlrev_b32_e32 v24, 16, v7
	v_mul_f32_e32 v21, 0x45800000, v20
	v_cndmask_b32_e32 v20, v20, v21, vcc
	v_pk_mul_f32 v[18:19], v[18:19], v[20:21] op_sel_hi:[1,0]
	v_pk_mul_f32 v[20:21], v[34:35], v[20:21] op_sel_hi:[1,0]
	v_pk_mul_f32 v[16:17], v[16:17], v[18:19]
	v_mul_f32_e32 v18, 0xbfb8aa3b, v36
	v_mul_f32_e32 v19, 0xbfb8aa3b, v37
	v_exp_f32_e32 v18, v18
	v_exp_f32_e32 v19, v19
	v_cvt_pk_bf16_f32 v16, v16, v17
	v_and_b32_e32 v7, 0xffff0000, v6
	v_add_f32_e32 v18, 1.0, v18
	v_add_f32_e32 v19, 1.0, v19
	v_rcp_f32_e32 v18, v18
	v_rcp_f32_e32 v19, v19
	v_lshlrev_b32_e32 v6, 16, v6
	v_mul_f32_e32 v28, 0xbfb8aa3b, v6
	v_mul_f32_e32 v29, 0xbfb8aa3b, v7
	v_pk_mul_f32 v[18:19], v[18:19], v[36:37]
	v_exp_f32_e32 v28, v28
	v_pk_mul_f32 v[18:19], v[18:19], v[20:21]
	v_exp_f32_e32 v29, v29
	v_cvt_pk_bf16_f32 v17, v18, v19
	flat_store_dwordx2 v[10:11], v[16:17] offset:2048
	v_and_b32_e32 v17, 0xffff0000, v15
	v_lshlrev_b32_e32 v16, 16, v15
	v_and_b32_e32 v15, 0xffff0000, v14
	v_lshlrev_b32_e32 v14, 16, v14
	v_mul_f32_e32 v22, 0xbfb8aa3b, v16
	v_mul_f32_e32 v23, 0xbfb8aa3b, v17
	v_mul_f32_e32 v18, 0xbfb8aa3b, v14
	v_mul_f32_e32 v19, 0xbfb8aa3b, v15
	v_exp_f32_e32 v22, v22
	v_exp_f32_e32 v23, v23
	v_exp_f32_e32 v18, v18
	v_exp_f32_e32 v19, v19
	v_add_f32_e32 v22, 1.0, v22
	v_add_f32_e32 v23, 1.0, v23
	v_add_f32_e32 v18, 1.0, v18
	v_add_f32_e32 v19, 1.0, v19
	v_rcp_f32_e32 v22, v22
	v_rcp_f32_e32 v23, v23
	v_add_f32_e32 v28, 1.0, v28
	v_add_f32_e32 v29, 1.0, v29
	v_rcp_f32_e32 v18, v18
	v_rcp_f32_e32 v19, v19
	v_rcp_f32_e32 v28, v28
	v_rcp_f32_e32 v29, v29
	v_and_b32_e32 v11, 0xffff0000, v13
	v_lshlrev_b32_e32 v10, 16, v13
	v_and_b32_e32 v13, 0xffff0000, v12
	v_lshlrev_b32_e32 v12, 16, v12
	v_pk_mul_f32 v[16:17], v[22:23], v[16:17]
	v_and_b32_e32 v23, 0xffff0000, v9
	v_lshlrev_b32_e32 v22, 16, v9
	v_and_b32_e32 v9, 0xffff0000, v8
	v_lshlrev_b32_e32 v8, 16, v8
	v_pk_mul_f32 v[14:15], v[18:19], v[14:15]
	v_add_f32_e32 v18, v13, v12
	v_pk_mul_f32 v[6:7], v[28:29], v[6:7]
	v_add_f32_e32 v28, v9, v8
	v_add_f32_e32 v18, v18, v10
	v_add_f32_e32 v28, v28, v22
	v_add_f32_e32 v18, v18, v11
	v_add_f32_e32 v28, v28, v23
	s_nop 1
	v_add_f32_dpp v18, v18, v18 quad_perm:[1,0,3,2] row_mask:0xf bank_mask:0xf
	v_add_f32_dpp v28, v28, v28 quad_perm:[1,0,3,2] row_mask:0xf bank_mask:0xf
	s_nop 1
	v_add_f32_dpp v18, v18, v18 quad_perm:[2,3,0,1] row_mask:0xf bank_mask:0xf
	v_add_f32_dpp v28, v28, v28 quad_perm:[2,3,0,1] row_mask:0xf bank_mask:0xf
	s_nop 1
	v_add_f32_dpp v18, v18, v18 row_half_mirror row_mask:0xf bank_mask:0xf
	v_add_f32_dpp v28, v28, v28 row_half_mirror row_mask:0xf bank_mask:0xf
	s_nop 1
	v_add_f32_dpp v18, v18, v18 row_mirror row_mask:0xf bank_mask:0xf
	v_add_f32_dpp v28, v28, v28 row_mirror row_mask:0xf bank_mask:0xf
	v_mov_b32_e32 v19, v18
	v_mov_b32_e32 v29, v28
	s_nop 1
	v_permlane16_swap_b32_e32 v18, v19
	v_permlane16_swap_b32_e32 v28, v29
	v_add_f32_e32 v18, v18, v19
	v_add_f32_e32 v28, v28, v29
	v_mov_b32_e32 v19, v18
	v_mov_b32_e32 v29, v28
	s_nop 1
	v_permlane32_swap_b32_e32 v18, v19
	v_permlane32_swap_b32_e32 v28, v29
	v_add_f32_e32 v18, v18, v19
	v_add_f32_e32 v28, v28, v29
	v_mul_f32_e32 v18, 0x3b800000, v18
	v_mul_f32_e32 v28, 0x3b800000, v28
	v_pk_add_f32 v[12:13], v[12:13], v[18:19] op_sel_hi:[1,0] neg_lo:[0,1] neg_hi:[0,1]
	v_pk_add_f32 v[8:9], v[8:9], v[28:29] op_sel_hi:[1,0] neg_lo:[0,1] neg_hi:[0,1]
	v_pk_add_f32 v[10:11], v[10:11], v[18:19] op_sel_hi:[1,0] neg_lo:[0,1] neg_hi:[0,1]
	v_pk_mul_f32 v[18:19], v[12:13], v[12:13]
	v_pk_add_f32 v[22:23], v[22:23], v[28:29] op_sel_hi:[1,0] neg_lo:[0,1] neg_hi:[0,1]
	v_pk_mul_f32 v[28:29], v[8:9], v[8:9]
	v_pk_mul_f32 v[20:21], v[10:11], v[10:11]
	v_pk_mul_f32 v[30:31], v[22:23], v[22:23]
	v_mov_b32_e32 v32, v28
	v_mov_b32_e32 v33, v18
	v_mov_b32_e32 v18, v29
	v_pk_add_f32 v[18:19], v[32:33], v[18:19]
	v_mov_b32_e32 v28, v30
	v_mov_b32_e32 v29, v20
	v_pk_add_f32 v[18:19], v[28:29], v[18:19]
	v_mov_b32_e32 v20, v31
	v_pk_add_f32 v[18:19], v[20:21], v[18:19]
	s_nop 1
	v_add_f32_dpp v18, v18, v18 quad_perm:[1,0,3,2] row_mask:0xf bank_mask:0xf
	v_add_f32_dpp v19, v19, v19 quad_perm:[1,0,3,2] row_mask:0xf bank_mask:0xf
	s_nop 1
	v_add_f32_dpp v18, v18, v18 quad_perm:[2,3,0,1] row_mask:0xf bank_mask:0xf
	v_add_f32_dpp v19, v19, v19 quad_perm:[2,3,0,1] row_mask:0xf bank_mask:0xf
	s_nop 1
	v_add_f32_dpp v18, v18, v18 row_half_mirror row_mask:0xf bank_mask:0xf
	v_add_f32_dpp v19, v19, v19 row_half_mirror row_mask:0xf bank_mask:0xf
	s_nop 1
	v_add_f32_dpp v18, v18, v18 row_mirror row_mask:0xf bank_mask:0xf
	v_add_f32_dpp v19, v19, v19 row_mirror row_mask:0xf bank_mask:0xf
	v_mov_b32_e32 v20, v18
	v_mov_b32_e32 v21, v19
	s_nop 1
	v_permlane16_swap_b32_e32 v18, v20
	v_permlane16_swap_b32_e32 v19, v21
	v_add_f32_e32 v18, v18, v20
	v_add_f32_e32 v19, v19, v21
	v_mov_b32_e32 v20, v18
	v_mov_b32_e32 v21, v19
	s_nop 1
	v_permlane32_swap_b32_e32 v18, v20
	v_permlane32_swap_b32_e32 v19, v21
	v_add_f32_e32 v18, v18, v20
	v_add_f32_e32 v19, v19, v21
	s_nop 0
	v_pk_fma_f32 v[18:19], v[18:19], s[28:29], v[26:27] op_sel_hi:[1,0,0]
	s_nop 0
	v_mul_f32_e32 v20, 0x4b800000, v19
	v_cmp_gt_f32_e64 s[20:21], s39, v19
	v_cmp_gt_f32_e32 vcc, s39, v18
	s_nop 0
	v_cndmask_b32_e64 v19, v19, v20, s[20:21]
	v_rsq_f32_e32 v19, v19
	s_nop 0
	v_mul_f32_e32 v20, 0x45800000, v19
	v_cndmask_b32_e64 v20, v19, v20, s[20:21]
	v_pk_mul_f32 v[12:13], v[12:13], v[20:21] op_sel_hi:[1,0]
	v_pk_mul_f32 v[10:11], v[10:11], v[20:21] op_sel_hi:[1,0]
	v_pk_mul_f32 v[12:13], v[14:15], v[12:13]
	v_pk_mul_f32 v[10:11], v[16:17], v[10:11]
	v_cvt_pk_bf16_f32 v12, v12, v13
	v_cvt_pk_bf16_f32 v13, v10, v11
	v_mul_f32_e32 v10, 0x4b800000, v18
	v_cndmask_b32_e32 v10, v18, v10, vcc
	v_rsq_f32_e32 v10, v10
	flat_store_dwordx2 v[4:5], v[12:13]
	v_mul_f32_e32 v11, 0x45800000, v10
	v_cndmask_b32_e32 v10, v10, v11, vcc
	v_pk_mul_f32 v[8:9], v[8:9], v[10:11] op_sel_hi:[1,0]
	v_pk_mul_f32 v[10:11], v[22:23], v[10:11] op_sel_hi:[1,0]
	v_pk_mul_f32 v[6:7], v[6:7], v[8:9]
	v_mul_f32_e32 v8, 0xbfb8aa3b, v24
	v_mul_f32_e32 v9, 0xbfb8aa3b, v25
	v_exp_f32_e32 v8, v8
	v_exp_f32_e32 v9, v9
	v_cvt_pk_bf16_f32 v6, v6, v7
	v_add_f32_e32 v8, 1.0, v8
	v_add_f32_e32 v9, 1.0, v9
	v_rcp_f32_e32 v8, v8
	v_rcp_f32_e32 v9, v9
	s_nop 0
	v_pk_mul_f32 v[8:9], v[8:9], v[24:25]
	s_nop 0
	v_pk_mul_f32 v[8:9], v[8:9], v[10:11]
	s_nop 0
	v_cvt_pk_bf16_f32 v7, v8, v9
	flat_store_dwordx2 v[4:5], v[6:7] offset:2048
	s_cbranch_scc0 .Lgpf_done
.Lgpf_loop:
	v_lshl_add_u64 v[4:5], v[2:3], 0, s[30:31]
	v_add_co_u32_e32 v6, vcc, 0x10800000, v4
	v_lshl_add_u64 v[8:9], v[0:1], 0, s[30:31]
	s_nop 0
	v_addc_co_u32_e32 v7, vcc, 0, v5, vcc
	v_add_co_u32_e32 v32, vcc, 0x18800000, v8
	s_nop 0
	v_addc_co_u32_e32 v33, vcc, 0, v9, vcc
	v_add_co_u32_e32 v6, vcc, 0x10801000, v4
	s_mov_b32 s20, 0x358637bd
	s_nop 0
	v_addc_co_u32_e32 v7, vcc, 0, v5, vcc
	v_add_co_u32_e32 v20, vcc, 0x18801000, v8
	s_nop 0
	v_addc_co_u32_e32 v21, vcc, 0, v9, vcc
	v_add_co_u32_e32 v6, vcc, 0x10802000, v4
	s_add_u32 s30, s30, 0x4000
	s_nop 0
	v_addc_co_u32_e32 v7, vcc, 0, v5, vcc
	v_add_co_u32_e32 v10, vcc, 0x18802000, v8
	s_nop 0
	v_addc_co_u32_e32 v11, vcc, 0, v9, vcc
	v_add_co_u32_e32 v6, vcc, 0x10803000, v4
	s_addc_u32 s31, s31, 0
	s_nop 0
	v_addc_co_u32_e32 v7, vcc, 0, v5, vcc
	v_add_co_u32_e32 v4, vcc, 0x18803000, v8
	s_nop 0
	v_addc_co_u32_e32 v5, vcc, 0, v9, vcc
	s_nop 0
	s_cmp_lg_u32 s30, 0x10000
	s_waitcnt vmcnt(0) lgkmcnt(0)
	v_mov_b32_e32 v26, v206
	v_mov_b32_e32 v27, v207
	v_mov_b32_e32 v38, v208
	v_mov_b32_e32 v39, v209
	v_mov_b32_e32 v40, v210
	v_mov_b32_e32 v41, v211
	v_mov_b32_e32 v42, v216
	v_mov_b32_e32 v43, v217
	v_mov_b32_e32 v34, v218
	v_mov_b32_e32 v35, v219
	v_mov_b32_e32 v36, v220
	v_mov_b32_e32 v37, v221
	v_mov_b32_e32 v30, v222
	v_mov_b32_e32 v31, v223
	v_mov_b32_e32 v28, v224
	v_mov_b32_e32 v29, v225
	v_mov_b32_e32 v22, v226
	v_mov_b32_e32 v23, v227
	v_mov_b32_e32 v24, v228
	v_mov_b32_e32 v25, v229
	v_mov_b32_e32 v18, v230
	v_mov_b32_e32 v19, v231
	v_mov_b32_e32 v16, v232
	v_mov_b32_e32 v17, v233
	v_mov_b32_e32 v12, v234
	v_mov_b32_e32 v13, v235
	v_mov_b32_e32 v14, v236
	v_mov_b32_e32 v15, v237
	v_mov_b32_e32 v8, v240
	v_mov_b32_e32 v9, v241
	v_mov_b32_e32 v6, v242
	v_mov_b32_e32 v7, v243
	s_cbranch_scc0 .Lgpf_skip_b
	v_lshl_add_u64 v[130:131], v[2:3], 0, s[30:31]
	v_add_co_u32_e32 v242, vcc, 0x10800000, v130
	v_lshl_add_u64 v[240:241], v[0:1], 0, s[30:31]
	s_nop 0
	v_addc_co_u32_e32 v243, vcc, 0, v131, vcc
	v_add_co_u32_e32 v134, vcc, 0x18800000, v240
	global_load_dwordx2 v[206:207], v[242:243], off
	s_nop 0
	v_addc_co_u32_e32 v135, vcc, 0, v241, vcc
	global_load_dwordx2 v[208:209], v[134:135], off
	global_load_dwordx2 v[210:211], v[242:243], off offset:2048
	global_load_dwordx2 v[216:217], v[134:135], off offset:2048
	v_add_co_u32_e32 v242, vcc, 0x10801000, v130
	s_nop 0
	v_addc_co_u32_e32 v243, vcc, 0, v131, vcc
	v_add_co_u32_e32 v136, vcc, 0x18801000, v240
	global_load_dwordx2 v[218:219], v[242:243], off
	s_nop 0
	v_addc_co_u32_e32 v137, vcc, 0, v241, vcc
	global_load_dwordx2 v[220:221], v[136:137], off
	global_load_dwordx2 v[222:223], v[242:243], off offset:2048
	global_load_dwordx2 v[224:225], v[136:137], off offset:2048
	v_add_co_u32_e32 v242, vcc, 0x10802000, v130
	s_nop 0
	v_addc_co_u32_e32 v243, vcc, 0, v131, vcc
	v_add_co_u32_e32 v138, vcc, 0x18802000, v240
	global_load_dwordx2 v[226:227], v[242:243], off
	s_nop 0
	v_addc_co_u32_e32 v139, vcc, 0, v241, vcc
	global_load_dwordx2 v[228:229], v[138:139], off
	global_load_dwordx2 v[230:231], v[242:243], off offset:2048
	global_load_dwordx2 v[232:233], v[138:139], off offset:2048
	v_add_co_u32_e32 v242, vcc, 0x10803000, v130
	s_nop 0
	v_addc_co_u32_e32 v243, vcc, 0, v131, vcc
	v_add_co_u32_e32 v130, vcc, 0x18803000, v240
	global_load_dwordx2 v[234:235], v[242:243], off
	s_nop 0
	v_addc_co_u32_e32 v131, vcc, 0, v241, vcc
	global_load_dwordx2 v[236:237], v[130:131], off
	global_load_dwordx2 v[240:241], v[242:243], off offset:2048
	s_nop 0
	global_load_dwordx2 v[242:243], v[130:131], off offset:2048
.Lgpf_skip_b:
	v_and_b32_e32 v45, 0xffff0000, v27
	v_and_b32_e32 v47, 0xffff0000, v39
	v_lshlrev_b32_e32 v46, 16, v39
	v_and_b32_e32 v39, 0xffff0000, v38
	v_lshlrev_b32_e32 v38, 16, v38
	v_mul_f32_e32 v52, 0xbfb8aa3b, v46
	v_mul_f32_e32 v53, 0xbfb8aa3b, v47
	v_and_b32_e32 v55, 0xffff0000, v43
	v_lshlrev_b32_e32 v54, 16, v43
	v_and_b32_e32 v43, 0xffff0000, v42
	v_lshlrev_b32_e32 v42, 16, v42
	v_mul_f32_e32 v48, 0xbfb8aa3b, v38
	v_mul_f32_e32 v49, 0xbfb8aa3b, v39
	v_exp_f32_e32 v52, v52
	v_exp_f32_e32 v53, v53
	v_mul_f32_e32 v56, 0xbfb8aa3b, v42
	v_mul_f32_e32 v57, 0xbfb8aa3b, v43
	v_exp_f32_e32 v48, v48
	v_exp_f32_e32 v49, v49
	v_exp_f32_e32 v56, v56
	v_exp_f32_e32 v57, v57
	v_add_f32_e32 v52, 1.0, v52
	v_add_f32_e32 v53, 1.0, v53
	v_add_f32_e32 v48, 1.0, v48
	v_add_f32_e32 v49, 1.0, v49
	v_rcp_f32_e32 v52, v52
	v_rcp_f32_e32 v53, v53
	v_add_f32_e32 v56, 1.0, v56
	v_add_f32_e32 v57, 1.0, v57
	v_rcp_f32_e32 v48, v48
	v_rcp_f32_e32 v49, v49
	v_rcp_f32_e32 v56, v56
	v_rcp_f32_e32 v57, v57
	v_lshlrev_b32_e32 v44, 16, v27
	v_and_b32_e32 v27, 0xffff0000, v26
	v_lshlrev_b32_e32 v26, 16, v26
	v_pk_mul_f32 v[46:47], v[52:53], v[46:47]
	v_and_b32_e32 v53, 0xffff0000, v41
	v_lshlrev_b32_e32 v52, 16, v41
	v_and_b32_e32 v41, 0xffff0000, v40
	v_lshlrev_b32_e32 v40, 16, v40
	v_pk_mul_f32 v[38:39], v[48:49], v[38:39]
	v_add_f32_e32 v48, v27, v26
	v_pk_mul_f32 v[42:43], v[56:57], v[42:43]
	v_add_f32_e32 v56, v41, v40
	v_add_f32_e32 v48, v48, v44
	v_add_f32_e32 v56, v56, v52
	v_add_f32_e32 v48, v48, v45
	v_add_f32_e32 v56, v56, v53
	s_nop 1
	v_add_f32_dpp v48, v48, v48 quad_perm:[1,0,3,2] row_mask:0xf bank_mask:0xf
	v_add_f32_dpp v56, v56, v56 quad_perm:[1,0,3,2] row_mask:0xf bank_mask:0xf
	s_nop 1
	v_add_f32_dpp v48, v48, v48 quad_perm:[2,3,0,1] row_mask:0xf bank_mask:0xf
	v_add_f32_dpp v56, v56, v56 quad_perm:[2,3,0,1] row_mask:0xf bank_mask:0xf
	s_nop 1
	v_add_f32_dpp v48, v48, v48 row_half_mirror row_mask:0xf bank_mask:0xf
	v_add_f32_dpp v56, v56, v56 row_half_mirror row_mask:0xf bank_mask:0xf
	s_nop 1
	v_add_f32_dpp v48, v48, v48 row_mirror row_mask:0xf bank_mask:0xf
	v_add_f32_dpp v56, v56, v56 row_mirror row_mask:0xf bank_mask:0xf
	v_mov_b32_e32 v49, v48
	v_mov_b32_e32 v57, v56
	s_nop 1
	v_permlane16_swap_b32_e32 v48, v49
	v_permlane16_swap_b32_e32 v56, v57
	v_add_f32_e32 v48, v48, v49
	v_add_f32_e32 v56, v56, v57
	v_mov_b32_e32 v49, v48
	v_mov_b32_e32 v57, v56
	s_nop 1
	v_permlane32_swap_b32_e32 v48, v49
	v_permlane32_swap_b32_e32 v56, v57
	v_add_f32_e32 v48, v48, v49
	v_add_f32_e32 v56, v56, v57
	v_mul_f32_e32 v48, 0x3b800000, v48
	v_mul_f32_e32 v56, 0x3b800000, v56
	v_pk_add_f32 v[50:51], v[26:27], v[48:49] op_sel_hi:[1,0] neg_lo:[0,1] neg_hi:[0,1]
	v_pk_add_f32 v[40:41], v[40:41], v[56:57] op_sel_hi:[1,0] neg_lo:[0,1] neg_hi:[0,1]
	v_pk_add_f32 v[44:45], v[44:45], v[48:49] op_sel_hi:[1,0] neg_lo:[0,1] neg_hi:[0,1]
	v_pk_mul_f32 v[26:27], v[50:51], v[50:51]
	v_pk_add_f32 v[52:53], v[52:53], v[56:57] op_sel_hi:[1,0] neg_lo:[0,1] neg_hi:[0,1]
	v_pk_mul_f32 v[56:57], v[40:41], v[40:41]
	v_pk_mul_f32 v[48:49], v[44:45], v[44:45]
	v_pk_mul_f32 v[58:59], v[52:53], v[52:53]
	v_mov_b32_e32 v60, v56
	v_mov_b32_e32 v61, v26
	v_mov_b32_e32 v26, v57
	v_pk_add_f32 v[26:27], v[60:61], v[26:27]
	v_mov_b32_e32 v56, v58
	v_mov_b32_e32 v57, v48
	v_pk_add_f32 v[26:27], v[56:57], v[26:27]
	v_mov_b32_e32 v48, v59
	v_pk_add_f32 v[26:27], v[48:49], v[26:27]
	s_nop 1
	v_add_f32_dpp v26, v26, v26 quad_perm:[1,0,3,2] row_mask:0xf bank_mask:0xf
	v_add_f32_dpp v27, v27, v27 quad_perm:[1,0,3,2] row_mask:0xf bank_mask:0xf
	s_nop 1
	v_add_f32_dpp v26, v26, v26 quad_perm:[2,3,0,1] row_mask:0xf bank_mask:0xf
	v_add_f32_dpp v27, v27, v27 quad_perm:[2,3,0,1] row_mask:0xf bank_mask:0xf
	s_nop 1
	v_add_f32_dpp v26, v26, v26 row_half_mirror row_mask:0xf bank_mask:0xf
	v_add_f32_dpp v27, v27, v27 row_half_mirror row_mask:0xf bank_mask:0xf
	s_nop 1
	v_add_f32_dpp v26, v26, v26 row_mirror row_mask:0xf bank_mask:0xf
	v_add_f32_dpp v27, v27, v27 row_mirror row_mask:0xf bank_mask:0xf
	v_mov_b32_e32 v48, v26
	v_mov_b32_e32 v49, v27
	s_nop 1
	v_permlane16_swap_b32_e32 v26, v48
	v_permlane16_swap_b32_e32 v27, v49
	v_add_f32_e32 v26, v26, v48
	v_add_f32_e32 v27, v27, v49
	v_mov_b32_e32 v48, v26
	v_mov_b32_e32 v49, v27
	s_nop 1
	v_permlane32_swap_b32_e32 v26, v48
	v_permlane32_swap_b32_e32 v27, v49
	v_add_f32_e32 v48, v26, v48
	v_add_f32_e32 v49, v27, v49
	v_mov_b64_e32 v[26:27], s[20:21]
	v_pk_fma_f32 v[48:49], v[48:49], s[28:29], v[26:27] op_sel_hi:[1,0,0]
	s_nop 0
	v_mul_f32_e32 v56, 0x4b800000, v49
	v_cmp_gt_f32_e32 vcc, s39, v49
	v_cmp_gt_f32_e64 s[20:21], s39, v48
	s_nop 0
	v_cndmask_b32_e32 v49, v49, v56, vcc
	v_rsq_f32_e32 v49, v49
	s_nop 0
	v_mul_f32_e32 v56, 0x45800000, v49
	v_cndmask_b32_e32 v56, v49, v56, vcc
	v_pk_mul_f32 v[50:51], v[50:51], v[56:57] op_sel_hi:[1,0]
	v_pk_mul_f32 v[44:45], v[44:45], v[56:57] op_sel_hi:[1,0]
	v_pk_mul_f32 v[38:39], v[38:39], v[50:51]
	v_pk_mul_f32 v[44:45], v[46:47], v[44:45]
	v_cvt_pk_bf16_f32 v38, v38, v39
	v_cvt_pk_bf16_f32 v39, v44, v45
	flat_store_dwordx2 v[32:33], v[38:39]
	v_mul_f32_e32 v38, 0x4b800000, v48
	v_cndmask_b32_e64 v38, v48, v38, s[20:21]
	v_rsq_f32_e32 v38, v38
	v_and_b32_e32 v47, 0xffff0000, v29
	v_lshlrev_b32_e32 v46, 16, v29
	v_and_b32_e32 v29, 0xffff0000, v28
	v_mul_f32_e32 v39, 0x45800000, v38
	v_cndmask_b32_e64 v38, v38, v39, s[20:21]
	v_pk_mul_f32 v[40:41], v[40:41], v[38:39] op_sel_hi:[1,0]
	v_mul_f32_e32 v39, 0xbfb8aa3b, v54
	v_pk_mul_f32 v[40:41], v[42:43], v[40:41]
	v_mul_f32_e32 v43, 0xbfb8aa3b, v55
	v_exp_f32_e32 v39, v39
	v_exp_f32_e32 v43, v43
	v_cvt_pk_bf16_f32 v40, v40, v41
	v_lshlrev_b32_e32 v28, 16, v28
	v_add_f32_e32 v39, 1.0, v39
	v_add_f32_e32 v43, 1.0, v43
	v_rcp_f32_e32 v42, v39
	v_rcp_f32_e32 v43, v43
	v_pk_mul_f32 v[38:39], v[52:53], v[38:39] op_sel_hi:[1,0]
	v_mul_f32_e32 v48, 0xbfb8aa3b, v28
	v_mul_f32_e32 v49, 0xbfb8aa3b, v29
	v_pk_mul_f32 v[42:43], v[42:43], v[54:55]
	v_exp_f32_e32 v48, v48
	v_pk_mul_f32 v[38:39], v[42:43], v[38:39]
	v_exp_f32_e32 v49, v49
	v_cvt_pk_bf16_f32 v41, v38, v39
	v_and_b32_e32 v39, 0xffff0000, v37
	v_lshlrev_b32_e32 v38, 16, v37
	v_and_b32_e32 v37, 0xffff0000, v36
	v_lshlrev_b32_e32 v36, 16, v36
	v_mul_f32_e32 v44, 0xbfb8aa3b, v38
	v_mul_f32_e32 v45, 0xbfb8aa3b, v39
	flat_store_dwordx2 v[32:33], v[40:41] offset:2048
	v_mul_f32_e32 v40, 0xbfb8aa3b, v36
	v_mul_f32_e32 v41, 0xbfb8aa3b, v37
	v_exp_f32_e32 v44, v44
	v_exp_f32_e32 v45, v45
	v_exp_f32_e32 v40, v40
	v_exp_f32_e32 v41, v41
	v_add_f32_e32 v44, 1.0, v44
	v_add_f32_e32 v45, 1.0, v45
	v_add_f32_e32 v40, 1.0, v40
	v_add_f32_e32 v41, 1.0, v41
	v_rcp_f32_e32 v44, v44
	v_rcp_f32_e32 v45, v45
	v_add_f32_e32 v48, 1.0, v48
	v_add_f32_e32 v49, 1.0, v49
	v_rcp_f32_e32 v40, v40
	v_rcp_f32_e32 v41, v41
	v_rcp_f32_e32 v48, v48
	v_rcp_f32_e32 v49, v49
	v_and_b32_e32 v33, 0xffff0000, v35
	v_lshlrev_b32_e32 v32, 16, v35
	v_and_b32_e32 v35, 0xffff0000, v34
	v_lshlrev_b32_e32 v34, 16, v34
	v_pk_mul_f32 v[38:39], v[44:45], v[38:39]
	v_and_b32_e32 v45, 0xffff0000, v31
	v_lshlrev_b32_e32 v44, 16, v31
	v_and_b32_e32 v31, 0xffff0000, v30
	v_lshlrev_b32_e32 v30, 16, v30
	v_pk_mul_f32 v[36:37], v[40:41], v[36:37]
	v_add_f32_e32 v40, v35, v34
	v_pk_mul_f32 v[28:29], v[48:49], v[28:29]
	v_add_f32_e32 v48, v31, v30
	v_add_f32_e32 v40, v40, v32
	v_add_f32_e32 v48, v48, v44
	v_add_f32_e32 v40, v40, v33
	v_add_f32_e32 v48, v48, v45
	s_nop 1
	v_add_f32_dpp v40, v40, v40 quad_perm:[1,0,3,2] row_mask:0xf bank_mask:0xf
	v_add_f32_dpp v48, v48, v48 quad_perm:[1,0,3,2] row_mask:0xf bank_mask:0xf
	s_nop 1
	v_add_f32_dpp v40, v40, v40 quad_perm:[2,3,0,1] row_mask:0xf bank_mask:0xf
	v_add_f32_dpp v48, v48, v48 quad_perm:[2,3,0,1] row_mask:0xf bank_mask:0xf
	s_nop 1
	v_add_f32_dpp v40, v40, v40 row_half_mirror row_mask:0xf bank_mask:0xf
	v_add_f32_dpp v48, v48, v48 row_half_mirror row_mask:0xf bank_mask:0xf
	s_nop 1
	v_add_f32_dpp v40, v40, v40 row_mirror row_mask:0xf bank_mask:0xf
	v_add_f32_dpp v48, v48, v48 row_mirror row_mask:0xf bank_mask:0xf
	v_mov_b32_e32 v41, v40
	v_mov_b32_e32 v49, v48
	s_nop 1
	v_permlane16_swap_b32_e32 v40, v41
	v_permlane16_swap_b32_e32 v48, v49
	v_add_f32_e32 v40, v40, v41
	v_add_f32_e32 v48, v48, v49
	v_mov_b32_e32 v41, v40
	v_mov_b32_e32 v49, v48
	s_nop 1
	v_permlane32_swap_b32_e32 v40, v41
	v_permlane32_swap_b32_e32 v48, v49
	v_add_f32_e32 v40, v40, v41
	v_add_f32_e32 v48, v48, v49
	v_mul_f32_e32 v40, 0x3b800000, v40
	v_mul_f32_e32 v48, 0x3b800000, v48
	v_pk_add_f32 v[34:35], v[34:35], v[40:41] op_sel_hi:[1,0] neg_lo:[0,1] neg_hi:[0,1]
	v_pk_add_f32 v[30:31], v[30:31], v[48:49] op_sel_hi:[1,0] neg_lo:[0,1] neg_hi:[0,1]
	v_pk_add_f32 v[32:33], v[32:33], v[40:41] op_sel_hi:[1,0] neg_lo:[0,1] neg_hi:[0,1]
	v_pk_mul_f32 v[40:41], v[34:35], v[34:35]
	v_pk_add_f32 v[44:45], v[44:45], v[48:49] op_sel_hi:[1,0] neg_lo:[0,1] neg_hi:[0,1]
	v_pk_mul_f32 v[48:49], v[30:31], v[30:31]
	v_pk_mul_f32 v[42:43], v[32:33], v[32:33]
	v_pk_mul_f32 v[50:51], v[44:45], v[44:45]
	v_mov_b32_e32 v52, v48
	v_mov_b32_e32 v53, v40
	v_mov_b32_e32 v40, v49
	v_pk_add_f32 v[40:41], v[52:53], v[40:41]
	v_mov_b32_e32 v48, v50
	v_mov_b32_e32 v49, v42
	v_pk_add_f32 v[40:41], v[48:49], v[40:41]
	v_mov_b32_e32 v42, v51
	v_pk_add_f32 v[40:41], v[42:43], v[40:41]
	s_nop 1
	v_add_f32_dpp v40, v40, v40 quad_perm:[1,0,3,2] row_mask:0xf bank_mask:0xf
	v_add_f32_dpp v41, v41, v41 quad_perm:[1,0,3,2] row_mask:0xf bank_mask:0xf
	s_nop 1
	v_add_f32_dpp v40, v40, v40 quad_perm:[2,3,0,1] row_mask:0xf bank_mask:0xf
	v_add_f32_dpp v41, v41, v41 quad_perm:[2,3,0,1] row_mask:0xf bank_mask:0xf
	s_nop 1
	v_add_f32_dpp v40, v40, v40 row_half_mirror row_mask:0xf bank_mask:0xf
	v_add_f32_dpp v41, v41, v41 row_half_mirror row_mask:0xf bank_mask:0xf
	s_nop 1
	v_add_f32_dpp v40, v40, v40 row_mirror row_mask:0xf bank_mask:0xf
	v_add_f32_dpp v41, v41, v41 row_mirror row_mask:0xf bank_mask:0xf
	v_mov_b32_e32 v42, v40
	v_mov_b32_e32 v43, v41
	s_nop 1
	v_permlane16_swap_b32_e32 v40, v42
	v_permlane16_swap_b32_e32 v41, v43
	v_add_f32_e32 v40, v40, v42
	v_add_f32_e32 v41, v41, v43
	v_mov_b32_e32 v42, v40
	v_mov_b32_e32 v43, v41
	s_nop 1
	v_permlane32_swap_b32_e32 v40, v42
	v_permlane32_swap_b32_e32 v41, v43
	v_add_f32_e32 v40, v40, v42
	v_add_f32_e32 v41, v41, v43
	s_nop 0
	v_pk_fma_f32 v[40:41], v[40:41], s[28:29], v[26:27] op_sel_hi:[1,0,0]
	s_nop 0
	v_mul_f32_e32 v42, 0x4b800000, v41
	v_cmp_gt_f32_e64 s[20:21], s39, v41
	v_cmp_gt_f32_e32 vcc, s39, v40
	s_nop 0
	v_cndmask_b32_e64 v41, v41, v42, s[20:21]
	v_rsq_f32_e32 v41, v41
	s_nop 0
	v_mul_f32_e32 v42, 0x45800000, v41
	v_cndmask_b32_e64 v42, v41, v42, s[20:21]
	v_pk_mul_f32 v[34:35], v[34:35], v[42:43] op_sel_hi:[1,0]
	v_pk_mul_f32 v[32:33], v[32:33], v[42:43] op_sel_hi:[1,0]
	v_pk_mul_f32 v[34:35], v[36:37], v[34:35]
	v_pk_mul_f32 v[32:33], v[38:39], v[32:33]
	v_cvt_pk_bf16_f32 v34, v34, v35
	v_cvt_pk_bf16_f32 v35, v32, v33
	v_mul_f32_e32 v32, 0x4b800000, v40
	v_cndmask_b32_e32 v32, v40, v32, vcc
	v_rsq_f32_e32 v32, v32
	flat_store_dwordx2 v[20:21], v[34:35]
	v_and_b32_e32 v37, 0xffff0000, v17
	v_lshlrev_b32_e32 v36, 16, v17
	v_mul_f32_e32 v33, 0x45800000, v32
	v_cndmask_b32_e32 v32, v32, v33, vcc
	v_pk_mul_f32 v[30:31], v[30:31], v[32:33] op_sel_hi:[1,0]
	v_pk_mul_f32 v[32:33], v[44:45], v[32:33] op_sel_hi:[1,0]
	v_pk_mul_f32 v[28:29], v[28:29], v[30:31]
	v_mul_f32_e32 v30, 0xbfb8aa3b, v46
	v_mul_f32_e32 v31, 0xbfb8aa3b, v47
	v_exp_f32_e32 v30, v30
	v_exp_f32_e32 v31, v31
	v_cvt_pk_bf16_f32 v28, v28, v29
	v_and_b32_e32 v17, 0xffff0000, v16
	v_add_f32_e32 v30, 1.0, v30
	v_add_f32_e32 v31, 1.0, v31
	v_rcp_f32_e32 v30, v30
	v_rcp_f32_e32 v31, v31
	v_lshlrev_b32_e32 v16, 16, v16
	v_mul_f32_e32 v38, 0xbfb8aa3b, v16
	v_mul_f32_e32 v39, 0xbfb8aa3b, v17
	v_pk_mul_f32 v[30:31], v[30:31], v[46:47]
	v_exp_f32_e32 v38, v38
	v_pk_mul_f32 v[30:31], v[30:31], v[32:33]
	v_exp_f32_e32 v39, v39
	v_cvt_pk_bf16_f32 v29, v30, v31
	flat_store_dwordx2 v[20:21], v[28:29] offset:2048
	v_and_b32_e32 v29, 0xffff0000, v25
	v_lshlrev_b32_e32 v28, 16, v25
	v_and_b32_e32 v25, 0xffff0000, v24
	v_lshlrev_b32_e32 v24, 16, v24
	v_mul_f32_e32 v34, 0xbfb8aa3b, v28
	v_mul_f32_e32 v35, 0xbfb8aa3b, v29
	v_mul_f32_e32 v30, 0xbfb8aa3b, v24
	v_mul_f32_e32 v31, 0xbfb8aa3b, v25
	v_exp_f32_e32 v34, v34
	v_exp_f32_e32 v35, v35
	v_exp_f32_e32 v30, v30
	v_exp_f32_e32 v31, v31
	v_add_f32_e32 v34, 1.0, v34
	v_add_f32_e32 v35, 1.0, v35
	v_add_f32_e32 v30, 1.0, v30
	v_add_f32_e32 v31, 1.0, v31
	v_rcp_f32_e32 v34, v34
	v_rcp_f32_e32 v35, v35
	v_add_f32_e32 v38, 1.0, v38
	v_add_f32_e32 v39, 1.0, v39
	v_rcp_f32_e32 v30, v30
	v_rcp_f32_e32 v31, v31
	v_rcp_f32_e32 v38, v38
	v_rcp_f32_e32 v39, v39
	v_and_b32_e32 v21, 0xffff0000, v23
	v_lshlrev_b32_e32 v20, 16, v23
	v_and_b32_e32 v23, 0xffff0000, v22
	v_lshlrev_b32_e32 v22, 16, v22
	v_pk_mul_f32 v[28:29], v[34:35], v[28:29]
	v_and_b32_e32 v35, 0xffff0000, v19
	v_lshlrev_b32_e32 v34, 16, v19
	v_and_b32_e32 v19, 0xffff0000, v18
	v_lshlrev_b32_e32 v18, 16, v18
	v_pk_mul_f32 v[24:25], v[30:31], v[24:25]
	v_add_f32_e32 v30, v23, v22
	v_pk_mul_f32 v[16:17], v[38:39], v[16:17]
	v_add_f32_e32 v38, v19, v18
	v_add_f32_e32 v30, v30, v20
	v_add_f32_e32 v38, v38, v34
	v_add_f32_e32 v30, v30, v21
	v_add_f32_e32 v38, v38, v35
	s_nop 1
	v_add_f32_dpp v30, v30, v30 quad_perm:[1,0,3,2] row_mask:0xf bank_mask:0xf
	v_add_f32_dpp v38, v38, v38 quad_perm:[1,0,3,2] row_mask:0xf bank_mask:0xf
	s_nop 1
	v_add_f32_dpp v30, v30, v30 quad_perm:[2,3,0,1] row_mask:0xf bank_mask:0xf
	v_add_f32_dpp v38, v38, v38 quad_perm:[2,3,0,1] row_mask:0xf bank_mask:0xf
	s_nop 1
	v_add_f32_dpp v30, v30, v30 row_half_mirror row_mask:0xf bank_mask:0xf
	v_add_f32_dpp v38, v38, v38 row_half_mirror row_mask:0xf bank_mask:0xf
	s_nop 1
	v_add_f32_dpp v30, v30, v30 row_mirror row_mask:0xf bank_mask:0xf
	v_add_f32_dpp v38, v38, v38 row_mirror row_mask:0xf bank_mask:0xf
	v_mov_b32_e32 v31, v30
	v_mov_b32_e32 v39, v38
	s_nop 1
	v_permlane16_swap_b32_e32 v30, v31
	v_permlane16_swap_b32_e32 v38, v39
	v_add_f32_e32 v30, v30, v31
	v_add_f32_e32 v38, v38, v39
	v_mov_b32_e32 v31, v30
	v_mov_b32_e32 v39, v38
	s_nop 1
	v_permlane32_swap_b32_e32 v30, v31
	v_permlane32_swap_b32_e32 v38, v39
	v_add_f32_e32 v30, v30, v31
	v_add_f32_e32 v38, v38, v39
	v_mul_f32_e32 v30, 0x3b800000, v30
	v_mul_f32_e32 v38, 0x3b800000, v38
	v_pk_add_f32 v[22:23], v[22:23], v[30:31] op_sel_hi:[1,0] neg_lo:[0,1] neg_hi:[0,1]
	v_pk_add_f32 v[18:19], v[18:19], v[38:39] op_sel_hi:[1,0] neg_lo:[0,1] neg_hi:[0,1]
	v_pk_add_f32 v[20:21], v[20:21], v[30:31] op_sel_hi:[1,0] neg_lo:[0,1] neg_hi:[0,1]
	v_pk_mul_f32 v[30:31], v[22:23], v[22:23]
	v_pk_add_f32 v[34:35], v[34:35], v[38:39] op_sel_hi:[1,0] neg_lo:[0,1] neg_hi:[0,1]
	v_pk_mul_f32 v[38:39], v[18:19], v[18:19]
	v_pk_mul_f32 v[32:33], v[20:21], v[20:21]
	v_pk_mul_f32 v[40:41], v[34:35], v[34:35]
	v_mov_b32_e32 v42, v38
	v_mov_b32_e32 v43, v30
	v_mov_b32_e32 v30, v39
	v_pk_add_f32 v[30:31], v[42:43], v[30:31]
	v_mov_b32_e32 v38, v40
	v_mov_b32_e32 v39, v32
	v_pk_add_f32 v[30:31], v[38:39], v[30:31]
	v_mov_b32_e32 v32, v41
	v_pk_add_f32 v[30:31], v[32:33], v[30:31]
	s_nop 1
	v_add_f32_dpp v30, v30, v30 quad_perm:[1,0,3,2] row_mask:0xf bank_mask:0xf
	v_add_f32_dpp v31, v31, v31 quad_perm:[1,0,3,2] row_mask:0xf bank_mask:0xf
	s_nop 1
	v_add_f32_dpp v30, v30, v30 quad_perm:[2,3,0,1] row_mask:0xf bank_mask:0xf
	v_add_f32_dpp v31, v31, v31 quad_perm:[2,3,0,1] row_mask:0xf bank_mask:0xf
	s_nop 1
	v_add_f32_dpp v30, v30, v30 row_half_mirror row_mask:0xf bank_mask:0xf
	v_add_f32_dpp v31, v31, v31 row_half_mirror row_mask:0xf bank_mask:0xf
	s_nop 1
	v_add_f32_dpp v30, v30, v30 row_mirror row_mask:0xf bank_mask:0xf
	v_add_f32_dpp v31, v31, v31 row_mirror row_mask:0xf bank_mask:0xf
	v_mov_b32_e32 v32, v30
	v_mov_b32_e32 v33, v31
	s_nop 1
	v_permlane16_swap_b32_e32 v30, v32
	v_permlane16_swap_b32_e32 v31, v33
	v_add_f32_e32 v30, v30, v32
	v_add_f32_e32 v31, v31, v33
	v_mov_b32_e32 v32, v30
	v_mov_b32_e32 v33, v31
	s_nop 1
	v_permlane32_swap_b32_e32 v30, v32
	v_permlane32_swap_b32_e32 v31, v33
	v_add_f32_e32 v30, v30, v32
	v_add_f32_e32 v31, v31, v33
	s_nop 0
	v_pk_fma_f32 v[30:31], v[30:31], s[28:29], v[26:27] op_sel_hi:[1,0,0]
	s_nop 0
	v_mul_f32_e32 v32, 0x4b800000, v31
	v_cmp_gt_f32_e64 s[20:21], s39, v31
	v_cmp_gt_f32_e32 vcc, s39, v30
	s_nop 0
	v_cndmask_b32_e64 v31, v31, v32, s[20:21]
	v_rsq_f32_e32 v31, v31
	s_nop 0
	v_mul_f32_e32 v32, 0x45800000, v31
	v_cndmask_b32_e64 v32, v31, v32, s[20:21]
	v_pk_mul_f32 v[22:23], v[22:23], v[32:33] op_sel_hi:[1,0]
	v_pk_mul_f32 v[20:21], v[20:21], v[32:33] op_sel_hi:[1,0]
	v_pk_mul_f32 v[22:23], v[24:25], v[22:23]
	v_pk_mul_f32 v[20:21], v[28:29], v[20:21]
	v_cvt_pk_bf16_f32 v22, v22, v23
	v_cvt_pk_bf16_f32 v23, v20, v21
	v_mul_f32_e32 v20, 0x4b800000, v30
	v_cndmask_b32_e32 v20, v30, v20, vcc
	v_rsq_f32_e32 v20, v20
	flat_store_dwordx2 v[10:11], v[22:23]
	v_and_b32_e32 v25, 0xffff0000, v7
	v_lshlrev_b32_e32 v24, 16, v7
	v_mul_f32_e32 v21, 0x45800000, v20
	v_cndmask_b32_e32 v20, v20, v21, vcc
	v_pk_mul_f32 v[18:19], v[18:19], v[20:21] op_sel_hi:[1,0]
	v_pk_mul_f32 v[20:21], v[34:35], v[20:21] op_sel_hi:[1,0]
	v_pk_mul_f32 v[16:17], v[16:17], v[18:19]
	v_mul_f32_e32 v18, 0xbfb8aa3b, v36
	v_mul_f32_e32 v19, 0xbfb8aa3b, v37
	v_exp_f32_e32 v18, v18
	v_exp_f32_e32 v19, v19
	v_cvt_pk_bf16_f32 v16, v16, v17
	v_and_b32_e32 v7, 0xffff0000, v6
	v_add_f32_e32 v18, 1.0, v18
	v_add_f32_e32 v19, 1.0, v19
	v_rcp_f32_e32 v18, v18
	v_rcp_f32_e32 v19, v19
	v_lshlrev_b32_e32 v6, 16, v6
	v_mul_f32_e32 v28, 0xbfb8aa3b, v6
	v_mul_f32_e32 v29, 0xbfb8aa3b, v7
	v_pk_mul_f32 v[18:19], v[18:19], v[36:37]
	v_exp_f32_e32 v28, v28
	v_pk_mul_f32 v[18:19], v[18:19], v[20:21]
	v_exp_f32_e32 v29, v29
	v_cvt_pk_bf16_f32 v17, v18, v19
	flat_store_dwordx2 v[10:11], v[16:17] offset:2048
	v_and_b32_e32 v17, 0xffff0000, v15
	v_lshlrev_b32_e32 v16, 16, v15
	v_and_b32_e32 v15, 0xffff0000, v14
	v_lshlrev_b32_e32 v14, 16, v14
	v_mul_f32_e32 v22, 0xbfb8aa3b, v16
	v_mul_f32_e32 v23, 0xbfb8aa3b, v17
	v_mul_f32_e32 v18, 0xbfb8aa3b, v14
	v_mul_f32_e32 v19, 0xbfb8aa3b, v15
	v_exp_f32_e32 v22, v22
	v_exp_f32_e32 v23, v23
	v_exp_f32_e32 v18, v18
	v_exp_f32_e32 v19, v19
	v_add_f32_e32 v22, 1.0, v22
	v_add_f32_e32 v23, 1.0, v23
	v_add_f32_e32 v18, 1.0, v18
	v_add_f32_e32 v19, 1.0, v19
	v_rcp_f32_e32 v22, v22
	v_rcp_f32_e32 v23, v23
	v_add_f32_e32 v28, 1.0, v28
	v_add_f32_e32 v29, 1.0, v29
	v_rcp_f32_e32 v18, v18
	v_rcp_f32_e32 v19, v19
	v_rcp_f32_e32 v28, v28
	v_rcp_f32_e32 v29, v29
	v_and_b32_e32 v11, 0xffff0000, v13
	v_lshlrev_b32_e32 v10, 16, v13
	v_and_b32_e32 v13, 0xffff0000, v12
	v_lshlrev_b32_e32 v12, 16, v12
	v_pk_mul_f32 v[16:17], v[22:23], v[16:17]
	v_and_b32_e32 v23, 0xffff0000, v9
	v_lshlrev_b32_e32 v22, 16, v9
	v_and_b32_e32 v9, 0xffff0000, v8
	v_lshlrev_b32_e32 v8, 16, v8
	v_pk_mul_f32 v[14:15], v[18:19], v[14:15]
	v_add_f32_e32 v18, v13, v12
	v_pk_mul_f32 v[6:7], v[28:29], v[6:7]
	v_add_f32_e32 v28, v9, v8
	v_add_f32_e32 v18, v18, v10
	v_add_f32_e32 v28, v28, v22
	v_add_f32_e32 v18, v18, v11
	v_add_f32_e32 v28, v28, v23
	s_nop 1
	v_add_f32_dpp v18, v18, v18 quad_perm:[1,0,3,2] row_mask:0xf bank_mask:0xf
	v_add_f32_dpp v28, v28, v28 quad_perm:[1,0,3,2] row_mask:0xf bank_mask:0xf
	s_nop 1
	v_add_f32_dpp v18, v18, v18 quad_perm:[2,3,0,1] row_mask:0xf bank_mask:0xf
	v_add_f32_dpp v28, v28, v28 quad_perm:[2,3,0,1] row_mask:0xf bank_mask:0xf
	s_nop 1
	v_add_f32_dpp v18, v18, v18 row_half_mirror row_mask:0xf bank_mask:0xf
	v_add_f32_dpp v28, v28, v28 row_half_mirror row_mask:0xf bank_mask:0xf
	s_nop 1
	v_add_f32_dpp v18, v18, v18 row_mirror row_mask:0xf bank_mask:0xf
	v_add_f32_dpp v28, v28, v28 row_mirror row_mask:0xf bank_mask:0xf
	v_mov_b32_e32 v19, v18
	v_mov_b32_e32 v29, v28
	s_nop 1
	v_permlane16_swap_b32_e32 v18, v19
	v_permlane16_swap_b32_e32 v28, v29
	v_add_f32_e32 v18, v18, v19
	v_add_f32_e32 v28, v28, v29
	v_mov_b32_e32 v19, v18
	v_mov_b32_e32 v29, v28
	s_nop 1
	v_permlane32_swap_b32_e32 v18, v19
	v_permlane32_swap_b32_e32 v28, v29
	v_add_f32_e32 v18, v18, v19
	v_add_f32_e32 v28, v28, v29
	v_mul_f32_e32 v18, 0x3b800000, v18
	v_mul_f32_e32 v28, 0x3b800000, v28
	v_pk_add_f32 v[12:13], v[12:13], v[18:19] op_sel_hi:[1,0] neg_lo:[0,1] neg_hi:[0,1]
	v_pk_add_f32 v[8:9], v[8:9], v[28:29] op_sel_hi:[1,0] neg_lo:[0,1] neg_hi:[0,1]
	v_pk_add_f32 v[10:11], v[10:11], v[18:19] op_sel_hi:[1,0] neg_lo:[0,1] neg_hi:[0,1]
	v_pk_mul_f32 v[18:19], v[12:13], v[12:13]
	v_pk_add_f32 v[22:23], v[22:23], v[28:29] op_sel_hi:[1,0] neg_lo:[0,1] neg_hi:[0,1]
	v_pk_mul_f32 v[28:29], v[8:9], v[8:9]
	v_pk_mul_f32 v[20:21], v[10:11], v[10:11]
	v_pk_mul_f32 v[30:31], v[22:23], v[22:23]
	v_mov_b32_e32 v32, v28
	v_mov_b32_e32 v33, v18
	v_mov_b32_e32 v18, v29
	v_pk_add_f32 v[18:19], v[32:33], v[18:19]
	v_mov_b32_e32 v28, v30
	v_mov_b32_e32 v29, v20
	v_pk_add_f32 v[18:19], v[28:29], v[18:19]
	v_mov_b32_e32 v20, v31
	v_pk_add_f32 v[18:19], v[20:21], v[18:19]
	s_nop 1
	v_add_f32_dpp v18, v18, v18 quad_perm:[1,0,3,2] row_mask:0xf bank_mask:0xf
	v_add_f32_dpp v19, v19, v19 quad_perm:[1,0,3,2] row_mask:0xf bank_mask:0xf
	s_nop 1
	v_add_f32_dpp v18, v18, v18 quad_perm:[2,3,0,1] row_mask:0xf bank_mask:0xf
	v_add_f32_dpp v19, v19, v19 quad_perm:[2,3,0,1] row_mask:0xf bank_mask:0xf
	s_nop 1
	v_add_f32_dpp v18, v18, v18 row_half_mirror row_mask:0xf bank_mask:0xf
	v_add_f32_dpp v19, v19, v19 row_half_mirror row_mask:0xf bank_mask:0xf
	s_nop 1
	v_add_f32_dpp v18, v18, v18 row_mirror row_mask:0xf bank_mask:0xf
	v_add_f32_dpp v19, v19, v19 row_mirror row_mask:0xf bank_mask:0xf
	v_mov_b32_e32 v20, v18
	v_mov_b32_e32 v21, v19
	s_nop 1
	v_permlane16_swap_b32_e32 v18, v20
	v_permlane16_swap_b32_e32 v19, v21
	v_add_f32_e32 v18, v18, v20
	v_add_f32_e32 v19, v19, v21
	v_mov_b32_e32 v20, v18
	v_mov_b32_e32 v21, v19
	s_nop 1
	v_permlane32_swap_b32_e32 v18, v20
	v_permlane32_swap_b32_e32 v19, v21
	v_add_f32_e32 v18, v18, v20
	v_add_f32_e32 v19, v19, v21
	s_nop 0
	v_pk_fma_f32 v[18:19], v[18:19], s[28:29], v[26:27] op_sel_hi:[1,0,0]
	s_nop 0
	v_mul_f32_e32 v20, 0x4b800000, v19
	v_cmp_gt_f32_e64 s[20:21], s39, v19
	v_cmp_gt_f32_e32 vcc, s39, v18
	s_nop 0
	v_cndmask_b32_e64 v19, v19, v20, s[20:21]
	v_rsq_f32_e32 v19, v19
	s_nop 0
	v_mul_f32_e32 v20, 0x45800000, v19
	v_cndmask_b32_e64 v20, v19, v20, s[20:21]
	v_pk_mul_f32 v[12:13], v[12:13], v[20:21] op_sel_hi:[1,0]
	v_pk_mul_f32 v[10:11], v[10:11], v[20:21] op_sel_hi:[1,0]
	v_pk_mul_f32 v[12:13], v[14:15], v[12:13]
	v_pk_mul_f32 v[10:11], v[16:17], v[10:11]
	v_cvt_pk_bf16_f32 v12, v12, v13
	v_cvt_pk_bf16_f32 v13, v10, v11
	v_mul_f32_e32 v10, 0x4b800000, v18
	v_cndmask_b32_e32 v10, v18, v10, vcc
	v_rsq_f32_e32 v10, v10
	flat_store_dwordx2 v[4:5], v[12:13]
	v_mul_f32_e32 v11, 0x45800000, v10
	v_cndmask_b32_e32 v10, v10, v11, vcc
	v_pk_mul_f32 v[8:9], v[8:9], v[10:11] op_sel_hi:[1,0]
	v_pk_mul_f32 v[10:11], v[22:23], v[10:11] op_sel_hi:[1,0]
	v_pk_mul_f32 v[6:7], v[6:7], v[8:9]
	v_mul_f32_e32 v8, 0xbfb8aa3b, v24
	v_mul_f32_e32 v9, 0xbfb8aa3b, v25
	v_exp_f32_e32 v8, v8
	v_exp_f32_e32 v9, v9
	v_cvt_pk_bf16_f32 v6, v6, v7
	v_add_f32_e32 v8, 1.0, v8
	v_add_f32_e32 v9, 1.0, v9
	v_rcp_f32_e32 v8, v8
	v_rcp_f32_e32 v9, v9
	s_nop 0
	v_pk_mul_f32 v[8:9], v[8:9], v[24:25]
	s_nop 0
	v_pk_mul_f32 v[8:9], v[8:9], v[10:11]
	s_nop 0
	v_cvt_pk_bf16_f32 v7, v8, v9
	flat_store_dwordx2 v[4:5], v[6:7] offset:2048
	s_cbranch_scc1 .Lgpf_loop
.Lgpf_done:
	v_add_u32_e32 v71, s33, v71
	s_movk_i32 s20, 0x3ff
	v_cmp_lt_i32_e32 vcc, s20, v71
	s_or_b64 s[26:27], vcc, s[26:27]
	v_add_u16_e32 v213, s33, v213
	s_andn2_b64 exec, exec, s[26:27]
	s_cbranch_execnz .LBB0_509
